# v5 + V-tile LDS commit issued before the row sums (fast MLA loop)
# speedup vs baseline: 1.0443x; 1.0049x over previous
.Lf_966:
	s_or_b64 exec, exec, s[44:45]
	s_mulk_i32 s6, 0x2400
	v_add_u32_e32 v2, s6, v215
	s_waitcnt vmcnt(0)
	ds_write_b128 v2, v[6:9] offset:26624
	v_pk_add_f32 v[244:245], v[88:89], v[90:91]
	v_pk_add_f32 v[246:247], v[92:93], v[94:95]
	v_pk_add_f32 v[244:245], v[244:245], v[112:113]
	v_pk_add_f32 v[246:247], v[246:247], v[114:115]
	v_pk_add_f32 v[244:245], v[244:245], v[116:117]
	v_pk_add_f32 v[246:247], v[246:247], v[118:119]
	v_pk_add_f32 v[244:245], v[244:245], v[120:121]
	v_pk_add_f32 v[246:247], v[246:247], v[122:123]
	v_pk_add_f32 v[244:245], v[244:245], v[124:125]
	v_pk_add_f32 v[246:247], v[246:247], v[126:127]
	v_pk_add_f32 v[244:245], v[244:245], v[140:141]
	v_pk_add_f32 v[246:247], v[246:247], v[142:143]
	v_pk_add_f32 v[244:245], v[244:245], v[246:247]
	v_add_f32_e32 v248, v244, v245
	v_add_f32_e32 v248, v80, v248
	v_add_f32_e32 v248, v87, v248
	v_add_f32_e32 v248, v106, v248
	v_add_f32_e32 v248, v139, v248
	v_add_f32_e32 v206, v206, v248
	v_pk_add_f32 v[244:245], v[12:13], v[14:15]
	v_pk_add_f32 v[246:247], v[82:83], v[84:85]
	v_pk_add_f32 v[244:245], v[244:245], v[96:97]
	v_pk_add_f32 v[246:247], v[246:247], v[98:99]
	v_pk_add_f32 v[244:245], v[244:245], v[100:101]
	v_pk_add_f32 v[246:247], v[246:247], v[102:103]
	v_pk_add_f32 v[244:245], v[244:245], v[104:105]
	v_pk_add_f32 v[246:247], v[246:247], v[128:129]
	v_pk_add_f32 v[244:245], v[244:245], v[130:131]
	v_pk_add_f32 v[246:247], v[246:247], v[132:133]
	v_pk_add_f32 v[244:245], v[244:245], v[134:135]
	v_pk_add_f32 v[246:247], v[246:247], v[136:137]
	v_pk_add_f32 v[244:245], v[244:245], v[246:247]
	v_add_f32_e32 v248, v244, v245
	v_add_f32_e32 v248, v11, v248
	v_add_f32_e32 v248, v86, v248
	v_add_f32_e32 v248, v138, v248
	v_add_f32_e32 v248, v237, v248
	v_add_f32_e32 v0, v0, v248
	v_lshl_add_u64 v[200:201], v[200:201], 0, s[10:11]
	s_cmp_eq_u32 s33, 63
	v_lshl_add_u64 v[202:203], v[202:203], 0, s[12:13]
	s_waitcnt lgkmcnt(0)
	s_barrier
	s_cbranch_scc1 .LBB0_970
	s_mov_b32 s24, s33
	s_branch .Lf_960
